# SSD: flag prefetch load moved after the staging vmcnt drain (both direction loops), on top of v21
# baseline (speedup 1.0000x reference)
.LBB0_1012:
	s_and_b32 s35, s47, 1
	s_lshl_b32 s24, s35, 10
	s_add_i32 s54, s24, 0
	s_add_i32 s54, s54, 0x22800
	v_lshlrev_b32_e32 v56, 2, v136
	s_waitcnt lgkmcnt(0)
	s_barrier
	s_waitcnt vmcnt(9)
	ds_write_b128 v152, v[0:3]
	s_waitcnt vmcnt(8)
	ds_write_b128 v152, v[4:7] offset:34816
	s_waitcnt vmcnt(7)
	ds_write_b128 v153, v[8:11]
	s_waitcnt vmcnt(6)
	ds_write_b128 v153, v[12:15] offset:34816
	s_waitcnt vmcnt(5)
	ds_write_b128 v154, v[16:19]
	s_waitcnt vmcnt(4)
	ds_write_b128 v154, v[20:23] offset:34816
	s_waitcnt vmcnt(3)
	ds_write_b128 v155, v[24:27]
	s_waitcnt vmcnt(2)
	ds_write_b128 v155, v[28:31] offset:34816
	s_waitcnt vmcnt(0)
	s_and_b64 s[100:101], s[90:91], exec
	s_cbranch_scc1 .Lmy_noflag_a
	s_lshl_b32 s100, s55, 5
	s_ashr_i32 s101, s100, 31
	s_add_u32 s100, s31, s100
	s_addc_u32 s101, s43, s101
	global_load_dword v66, v65, s[100:101] sc1

.LBB0_1134:
	s_and_b32 s83, s34, 1
	s_lshl_b32 s20, s83, 10
	s_add_i32 s35, s20, 0
	s_add_i32 s35, s35, 0x22800
	v_lshlrev_b32_e32 v56, 2, v138
	s_waitcnt lgkmcnt(0)
	s_barrier
	s_waitcnt vmcnt(9)
	ds_write_b128 v155, v[0:3]
	s_waitcnt vmcnt(8)
	ds_write_b128 v155, v[4:7] offset:34816
	s_waitcnt vmcnt(7)
	ds_write_b128 v156, v[8:11]
	s_waitcnt vmcnt(6)
	ds_write_b128 v156, v[12:15] offset:34816
	s_waitcnt vmcnt(5)
	ds_write_b128 v157, v[16:19]
	s_waitcnt vmcnt(4)
	ds_write_b128 v157, v[20:23] offset:34816
	s_waitcnt vmcnt(3)
	ds_write_b128 v158, v[24:27]
	s_waitcnt vmcnt(2)
	ds_write_b128 v158, v[28:31] offset:34816
	s_waitcnt vmcnt(0)
	s_and_b64 s[100:101], s[90:91], exec
	s_cbranch_scc1 .Lmy_noflag_b
	s_lshl_b32 s100, s34, 5
	s_add_u32 s100, s47, s100
	s_addc_u32 s101, s51, 0
	global_load_dword v66, v65, s[100:101] sc1

	.amdhsa_kernel _Z10fwd_kernel4Args
		.amdhsa_group_segment_fixed_size 0
		.amdhsa_private_segment_fixed_size 0
		.amdhsa_kernarg_size 456
		.amdhsa_user_sgpr_count 2
		.amdhsa_user_sgpr_dispatch_ptr 0
		.amdhsa_user_sgpr_queue_ptr 0
		.amdhsa_user_sgpr_kernarg_segment_ptr 1
		.amdhsa_user_sgpr_dispatch_id 0
		.amdhsa_user_sgpr_kernarg_preload_length 0
		.amdhsa_user_sgpr_kernarg_preload_offset 0
		.amdhsa_user_sgpr_private_segment_size 0
		.amdhsa_uses_dynamic_stack 0
		.amdhsa_enable_private_segment 0
		.amdhsa_system_sgpr_workgroup_id_x 1
		.amdhsa_system_sgpr_workgroup_id_y 0
		.amdhsa_system_sgpr_workgroup_id_z 0
		.amdhsa_system_sgpr_workgroup_info 0
		.amdhsa_system_vgpr_workitem_id 0
		.amdhsa_next_free_vgpr 256
		.amdhsa_next_free_sgpr 102
		.amdhsa_accum_offset 256
		.amdhsa_reserve_vcc 1
		.amdhsa_float_round_mode_32 0
		.amdhsa_float_round_mode_16_64 0
		.amdhsa_float_denorm_mode_32 3
		.amdhsa_float_denorm_mode_16_64 3
		.amdhsa_dx10_clamp 1
		.amdhsa_ieee_mode 1
		.amdhsa_fp16_overflow 0
		.amdhsa_tg_split 0
		.amdhsa_exception_fp_ieee_invalid_op 0
		.amdhsa_exception_fp_denorm_src 0
		.amdhsa_exception_fp_ieee_div_zero 0
		.amdhsa_exception_fp_ieee_overflow 0
		.amdhsa_exception_fp_ieee_underflow 0
		.amdhsa_exception_fp_ieee_inexact 0
		.amdhsa_exception_int_div_zero 0
	.end_amdhsa_kernel

amdhsa.kernels:
  - .agpr_count:     0
    .args:
      - .offset:         0
        .size:           200
        .value_kind:     by_value
      - .offset:         200
        .size:           4
        .value_kind:     hidden_block_count_x
      - .offset:         204
        .size:           4
        .value_kind:     hidden_block_count_y
      - .offset:         208
        .size:           4
        .value_kind:     hidden_block_count_z
      - .offset:         212
        .size:           2
        .value_kind:     hidden_group_size_x
      - .offset:         214
        .size:           2
        .value_kind:     hidden_group_size_y
      - .offset:         216
        .size:           2
        .value_kind:     hidden_group_size_z
      - .offset:         218
        .size:           2
        .value_kind:     hidden_remainder_x
      - .offset:         220
        .size:           2
        .value_kind:     hidden_remainder_y
      - .offset:         222
        .size:           2
        .value_kind:     hidden_remainder_z
      - .offset:         240
        .size:           8
        .value_kind:     hidden_global_offset_x
      - .offset:         248
        .size:           8
        .value_kind:     hidden_global_offset_y
      - .offset:         256
        .size:           8
        .value_kind:     hidden_global_offset_z
      - .offset:         264
        .size:           2
        .value_kind:     hidden_grid_dims
      - .offset:         320
        .size:           4
        .value_kind:     hidden_dynamic_lds_size
    .group_segment_fixed_size: 0
    .kernarg_segment_align: 8
    .kernarg_segment_size: 456
    .language:       OpenCL C
    .language_version:
      - 2
      - 0
    .max_flat_workgroup_size: 512
    .name:           _Z10fwd_kernel4Args
    .private_segment_fixed_size: 0
    .sgpr_count:     108
    .sgpr_spill_count: 195
    .symbol:         _Z10fwd_kernel4Args.kd
    .uniform_work_group_size: 1
    .uses_dynamic_stack: false
    .vgpr_count:     256
    .vgpr_spill_count: 0
    .wavefront_size: 64
